# P0 row loop: xor-1/2/4/8 butterfly steps of the 9 per-row wave sums via DPP (quad_perm / row_half_mirror / row_mirror) instead of ds_bpermute; lgkmcnt recounted
# baseline (speedup 1.0000x reference)
.LBB0_115:
	v_mul_f32_e32 v221, v61, v61
	v_mul_f32_e32 v222, v63, v63
	v_fmac_f32_e32 v221, v60, v60
	v_fmac_f32_e32 v222, v62, v62
	v_add_f32_e32 v221, v221, v222
	v_mul_f32_e32 v222, v57, v57
	s_waitcnt lgkmcnt(7)
	v_mul_f32_e32 v234, v59, v59
	v_fmac_f32_e32 v222, v56, v56
	v_fmac_f32_e32 v234, v58, v58
	v_add_f32_e32 v222, v222, v234
	v_add_f32_e32 v221, v221, v222
	v_mul_f32_e32 v222, v53, v53
	v_mul_f32_e32 v234, v55, v55
	v_fmac_f32_e32 v222, v52, v52
	v_fmac_f32_e32 v234, v54, v54
	v_add_f32_e32 v222, v222, v234
	v_add_f32_e32 v221, v221, v222
	v_mul_f32_e32 v222, v49, v49
	v_mul_f32_e32 v234, v51, v51
	v_fmac_f32_e32 v222, v48, v48
	v_fmac_f32_e32 v234, v50, v50
	v_add_f32_e32 v222, v222, v234
	v_add_f32_e32 v221, v221, v222
	s_nop 1
	v_mov_b32_dpp v222, v221 quad_perm:[1,0,3,2] row_mask:0xf bank_mask:0xf
	s_waitcnt lgkmcnt(7)
	v_mul_f32_e32 v234, v61, v65
	v_mul_f32_e32 v235, v63, v67
	v_fmac_f32_e32 v234, v60, v64
	v_fmac_f32_e32 v235, v62, v66
	s_waitcnt lgkmcnt(0)
	v_add_f32_e32 v221, v221, v222
	s_nop 1
	v_mov_b32_dpp v222, v221 quad_perm:[2,3,0,1] row_mask:0xf bank_mask:0xf
	v_add_f32_e32 v234, v234, v235
	v_mul_f32_e32 v235, v57, v69
	v_mul_f32_e32 v236, v59, v71
	v_fmac_f32_e32 v235, v56, v68
	s_waitcnt lgkmcnt(0)
	v_add_f32_e32 v221, v221, v222
	s_nop 1
	v_mov_b32_dpp v222, v221 row_half_mirror row_mask:0xf bank_mask:0xf
	v_fmac_f32_e32 v236, v58, v70
	v_add_f32_e32 v234, 0, v234
	v_add_f32_e32 v235, v235, v236
	v_add_f32_e32 v234, v234, v235
	s_waitcnt lgkmcnt(0)
	v_add_f32_e32 v221, v221, v222
	v_mul_f32_e32 v235, v53, v73
	v_mul_f32_e32 v236, v55, v75
	v_mov_b32_dpp v222, v221 row_mirror row_mask:0xf bank_mask:0xf
	v_fmac_f32_e32 v235, v52, v72
	v_fmac_f32_e32 v236, v54, v74
	v_add_f32_e32 v235, v235, v236
	v_add_f32_e32 v234, v234, v235
	v_mul_f32_e32 v235, v49, v77
	v_mul_f32_e32 v236, v51, v79
	v_fmac_f32_e32 v235, v48, v76
	v_fmac_f32_e32 v236, v50, v78
	v_add_f32_e32 v235, v235, v236
	s_waitcnt lgkmcnt(0)
	v_add_f32_e32 v221, v221, v222
	v_add_f32_e32 v234, v234, v235
	v_mul_f32_e32 v236, v61, v81
	v_mul_f32_e32 v237, v63, v83
	ds_bpermute_b32 v222, v229, v221
	v_mov_b32_dpp v235, v234 quad_perm:[1,0,3,2] row_mask:0xf bank_mask:0xf
	v_fmac_f32_e32 v236, v60, v80
	v_fmac_f32_e32 v237, v62, v82
	v_add_f32_e32 v236, v236, v237
	v_mul_f32_e32 v237, v57, v85
	v_mul_f32_e32 v238, v59, v87
	v_fmac_f32_e32 v237, v56, v84
	v_fmac_f32_e32 v238, v58, v86
	v_add_f32_e32 v236, 0, v236
	v_add_f32_e32 v237, v237, v238
	v_add_f32_e32 v236, v236, v237
	v_mul_f32_e32 v237, v53, v89
	v_mul_f32_e32 v238, v55, v91
	v_fmac_f32_e32 v237, v52, v88
	v_fmac_f32_e32 v238, v54, v90
	s_waitcnt lgkmcnt(0)
	v_add_f32_e32 v221, v221, v222
	s_waitcnt lgkmcnt(0)
	v_add_f32_e32 v234, v234, v235
	v_add_f32_e32 v237, v237, v238
	ds_bpermute_b32 v222, v230, v221
	v_mov_b32_dpp v235, v234 quad_perm:[2,3,0,1] row_mask:0xf bank_mask:0xf
	v_add_f32_e32 v236, v236, v237
	v_mul_f32_e32 v237, v49, v93
	v_mul_f32_e32 v238, v51, v95
	v_fmac_f32_e32 v237, v48, v92
	v_fmac_f32_e32 v238, v50, v94
	v_add_f32_e32 v237, v237, v238
	v_add_f32_e32 v236, v236, v237
	s_nop 1
	v_mov_b32_dpp v237, v236 quad_perm:[1,0,3,2] row_mask:0xf bank_mask:0xf
	s_waitcnt lgkmcnt(0)
	v_add_f32_e32 v221, v221, v222
	s_waitcnt lgkmcnt(0)
	v_add_f32_e32 v222, v234, v235
	s_nop 1
	v_mov_b32_dpp v234, v222 row_half_mirror row_mask:0xf bank_mask:0xf
	v_fmamk_f32 v221, v221, 0x3a800000, v209
	s_waitcnt lgkmcnt(0)
	v_add_f32_e32 v236, v236, v237
	s_nop 1
	v_mov_b32_dpp v237, v236 quad_perm:[2,3,0,1] row_mask:0xf bank_mask:0xf
	v_cmp_gt_f32_e64 s[0:1], s27, v221
	s_waitcnt lgkmcnt(0)
	v_add_f32_e32 v222, v222, v234
	s_nop 1
	v_mov_b32_dpp v234, v222 row_mirror row_mask:0xf bank_mask:0xf
	v_mul_f32_e32 v238, v63, v99
	s_waitcnt lgkmcnt(0)
	v_add_f32_e32 v235, v236, v237
	v_mul_f32_e32 v237, 0x4b800000, v221
	v_cndmask_b32_e64 v221, v221, v237, s[0:1]
	s_waitcnt lgkmcnt(0)
	v_add_f32_e32 v234, v222, v234
	v_rsq_f32_e32 v221, v221
	ds_bpermute_b32 v237, v229, v234
	v_fmac_f32_e32 v238, v62, v98
	v_mul_f32_e32 v239, v59, v103
	v_mul_f32_e32 v222, 0x45800000, v221
	v_cndmask_b32_e64 v222, v221, v222, s[0:1]
	s_waitcnt lgkmcnt(0)
	v_add_f32_e32 v221, v234, v237
	v_mul_f32_e32 v237, v61, v97
	v_fmac_f32_e32 v237, v60, v96
	v_add_f32_e32 v237, v237, v238
	v_mul_f32_e32 v238, v57, v101
	v_fmac_f32_e32 v238, v56, v100
	v_fmac_f32_e32 v239, v58, v102
	v_add_f32_e32 v237, 0, v237
	v_add_f32_e32 v238, v238, v239
	v_add_f32_e32 v237, v237, v238
	v_mul_f32_e32 v238, v53, v105
	v_mul_f32_e32 v239, v55, v107
	v_fmac_f32_e32 v238, v52, v104
	v_fmac_f32_e32 v239, v54, v106
	v_add_f32_e32 v238, v238, v239
	v_add_f32_e32 v237, v237, v238
	v_mul_f32_e32 v238, v49, v109
	v_mul_f32_e32 v239, v51, v111
	v_fmac_f32_e32 v238, v48, v108
	v_fmac_f32_e32 v239, v50, v110
	v_add_f32_e32 v238, v238, v239
	v_mul_f32_e32 v239, v61, v113
	v_mul_f32_e32 v240, v63, v115
	v_fmac_f32_e32 v239, v60, v112
	v_fmac_f32_e32 v240, v62, v114
	v_add_f32_e32 v239, v239, v240
	v_mul_f32_e32 v240, v57, v117
	v_mul_f32_e32 v241, v59, v119
	v_fmac_f32_e32 v240, v56, v116
	v_fmac_f32_e32 v241, v58, v118
	v_add_f32_e32 v239, 0, v239
	v_add_f32_e32 v240, v240, v241
	v_add_f32_e32 v239, v239, v240
	v_mul_f32_e32 v240, v53, v121
	v_mul_f32_e32 v241, v55, v123
	v_fmac_f32_e32 v240, v52, v120
	v_fmac_f32_e32 v241, v54, v122
	v_add_f32_e32 v240, v240, v241
	v_add_f32_e32 v239, v239, v240
	v_mul_f32_e32 v240, v49, v125
	v_mul_f32_e32 v241, v51, v127
	v_fmac_f32_e32 v240, v48, v124
	v_fmac_f32_e32 v241, v50, v126
	v_add_f32_e32 v240, v240, v241
	v_mul_f32_e32 v241, v61, v129
	v_mul_f32_e32 v242, v63, v131
	v_fmac_f32_e32 v241, v60, v128
	v_fmac_f32_e32 v242, v62, v130
	v_add_f32_e32 v241, v241, v242
	v_mul_f32_e32 v242, v57, v133
	v_mul_f32_e32 v243, v59, v135
	v_fmac_f32_e32 v242, v56, v132
	v_fmac_f32_e32 v243, v58, v134
	v_add_f32_e32 v241, 0, v241
	v_add_f32_e32 v242, v242, v243
	v_add_f32_e32 v241, v241, v242
	v_mul_f32_e32 v242, v53, v137
	v_mul_f32_e32 v243, v55, v139
	v_fmac_f32_e32 v242, v52, v136
	v_fmac_f32_e32 v243, v54, v138
	v_add_f32_e32 v242, v242, v243
	v_add_f32_e32 v241, v241, v242
	v_mul_f32_e32 v242, v49, v141
	v_mul_f32_e32 v243, v51, v143
	v_fmac_f32_e32 v242, v48, v140
	v_fmac_f32_e32 v243, v50, v142
	v_add_f32_e32 v242, v242, v243
	v_mul_f32_e32 v243, v61, v145
	v_mul_f32_e32 v244, v63, v147
	v_fmac_f32_e32 v243, v60, v144
	v_fmac_f32_e32 v244, v62, v146
	v_add_f32_e32 v243, v243, v244
	v_mul_f32_e32 v244, v57, v149
	v_mul_f32_e32 v245, v59, v151
	v_fmac_f32_e32 v244, v56, v148
	v_fmac_f32_e32 v245, v58, v150
	v_add_f32_e32 v243, 0, v243
	v_add_f32_e32 v244, v244, v245
	v_add_f32_e32 v243, v243, v244
	v_mul_f32_e32 v244, v53, v153
	v_mul_f32_e32 v245, v55, v155
	v_fmac_f32_e32 v244, v52, v152
	v_fmac_f32_e32 v245, v54, v154
	v_add_f32_e32 v244, v244, v245
	v_add_f32_e32 v243, v243, v244
	v_mul_f32_e32 v244, v49, v157
	v_mul_f32_e32 v245, v51, v159
	v_fmac_f32_e32 v244, v48, v156
	v_fmac_f32_e32 v245, v50, v158
	v_add_f32_e32 v244, v244, v245
	v_mul_f32_e32 v245, v61, v161
	v_mul_f32_e32 v246, v63, v163
	v_fmac_f32_e32 v245, v60, v160
	v_fmac_f32_e32 v246, v62, v162
	v_add_f32_e32 v245, v245, v246
	v_mul_f32_e32 v246, v57, v165
	v_mul_f32_e32 v247, v59, v167
	v_fmac_f32_e32 v246, v56, v164
	v_fmac_f32_e32 v247, v58, v166
	v_add_f32_e32 v245, 0, v245
	v_add_f32_e32 v246, v246, v247
	v_add_f32_e32 v245, v245, v246
	v_mul_f32_e32 v246, v53, v169
	v_mul_f32_e32 v247, v55, v171
	v_fmac_f32_e32 v246, v52, v168
	v_fmac_f32_e32 v247, v54, v170
	v_add_f32_e32 v246, v246, v247
	v_add_f32_e32 v245, v245, v246
	v_mul_f32_e32 v246, v49, v173
	v_mul_f32_e32 v247, v51, v175
	v_fmac_f32_e32 v246, v48, v172
	v_fmac_f32_e32 v247, v50, v174
	v_add_f32_e32 v246, v246, v247
	v_mul_f32_e32 v247, v61, v177
	v_mul_f32_e32 v248, v63, v179
	v_fmac_f32_e32 v247, v60, v176
	v_fmac_f32_e32 v248, v62, v178
	v_add_f32_e32 v247, v247, v248
	v_mul_f32_e32 v248, v57, v181
	v_mul_f32_e32 v249, v59, v183
	v_fmac_f32_e32 v248, v56, v180
	v_fmac_f32_e32 v249, v58, v182
	v_add_f32_e32 v247, 0, v247
	v_add_f32_e32 v248, v248, v249
	v_add_f32_e32 v247, v247, v248
	v_mul_f32_e32 v248, v53, v185
	v_mul_f32_e32 v249, v55, v187
	v_fmac_f32_e32 v248, v52, v184
	v_fmac_f32_e32 v249, v54, v186
	v_add_f32_e32 v248, v248, v249
	v_add_f32_e32 v247, v247, v248
	v_mul_f32_e32 v248, v49, v189
	v_mul_f32_e32 v249, v51, v191
	v_fmac_f32_e32 v248, v48, v188
	v_fmac_f32_e32 v249, v50, v190
	v_add_f32_e32 v248, v248, v249
	v_add_f32_e32 v237, v237, v238
	v_add_f32_e32 v239, v239, v240
	v_add_f32_e32 v241, v241, v242
	v_add_f32_e32 v243, v243, v244
	v_add_f32_e32 v245, v245, v246
	v_add_f32_e32 v247, v247, v248
	v_mov_b32_dpp v238, v237 quad_perm:[1,0,3,2] row_mask:0xf bank_mask:0xf
	v_mov_b32_dpp v240, v239 quad_perm:[1,0,3,2] row_mask:0xf bank_mask:0xf
	v_mov_b32_dpp v242, v241 quad_perm:[1,0,3,2] row_mask:0xf bank_mask:0xf
	v_mov_b32_dpp v244, v243 quad_perm:[1,0,3,2] row_mask:0xf bank_mask:0xf
	v_mov_b32_dpp v246, v245 quad_perm:[1,0,3,2] row_mask:0xf bank_mask:0xf
	v_mov_b32_dpp v248, v247 quad_perm:[1,0,3,2] row_mask:0xf bank_mask:0xf
	s_waitcnt lgkmcnt(0)
	v_add_f32_e32 v237, v237, v238
	s_waitcnt lgkmcnt(0)
	v_add_f32_e32 v239, v239, v240
	s_waitcnt lgkmcnt(0)
	v_add_f32_e32 v241, v241, v242
	s_waitcnt lgkmcnt(0)
	v_add_f32_e32 v243, v243, v244
	s_waitcnt lgkmcnt(0)
	v_add_f32_e32 v245, v245, v246
	s_waitcnt lgkmcnt(0)
	v_add_f32_e32 v247, v247, v248
	v_mov_b32_dpp v238, v237 quad_perm:[2,3,0,1] row_mask:0xf bank_mask:0xf
	v_mov_b32_dpp v240, v239 quad_perm:[2,3,0,1] row_mask:0xf bank_mask:0xf
	v_mov_b32_dpp v242, v241 quad_perm:[2,3,0,1] row_mask:0xf bank_mask:0xf
	v_mov_b32_dpp v244, v243 quad_perm:[2,3,0,1] row_mask:0xf bank_mask:0xf
	v_mov_b32_dpp v246, v245 quad_perm:[2,3,0,1] row_mask:0xf bank_mask:0xf
	v_mov_b32_dpp v248, v247 quad_perm:[2,3,0,1] row_mask:0xf bank_mask:0xf
	s_waitcnt lgkmcnt(0)
	v_add_f32_e32 v237, v237, v238
	s_waitcnt lgkmcnt(0)
	v_add_f32_e32 v239, v239, v240
	s_waitcnt lgkmcnt(0)
	v_add_f32_e32 v241, v241, v242
	s_waitcnt lgkmcnt(0)
	v_add_f32_e32 v243, v243, v244
	s_waitcnt lgkmcnt(0)
	v_add_f32_e32 v245, v245, v246
	s_waitcnt lgkmcnt(0)
	v_add_f32_e32 v247, v247, v248
	v_mov_b32_dpp v236, v235 row_half_mirror row_mask:0xf bank_mask:0xf
	v_mov_b32_dpp v238, v237 row_half_mirror row_mask:0xf bank_mask:0xf
	v_mov_b32_dpp v240, v239 row_half_mirror row_mask:0xf bank_mask:0xf
	v_mov_b32_dpp v242, v241 row_half_mirror row_mask:0xf bank_mask:0xf
	v_mov_b32_dpp v244, v243 row_half_mirror row_mask:0xf bank_mask:0xf
	v_mov_b32_dpp v246, v245 row_half_mirror row_mask:0xf bank_mask:0xf
	v_mov_b32_dpp v248, v247 row_half_mirror row_mask:0xf bank_mask:0xf
	s_waitcnt lgkmcnt(0)
	v_add_f32_e32 v235, v235, v236
	s_waitcnt lgkmcnt(0)
	v_add_f32_e32 v237, v237, v238
	s_waitcnt lgkmcnt(0)
	v_add_f32_e32 v239, v239, v240
	s_waitcnt lgkmcnt(0)
	v_add_f32_e32 v241, v241, v242
	s_waitcnt lgkmcnt(0)
	v_add_f32_e32 v243, v243, v244
	s_waitcnt lgkmcnt(0)
	v_add_f32_e32 v245, v245, v246
	s_waitcnt lgkmcnt(0)
	v_add_f32_e32 v247, v247, v248
	v_mov_b32_dpp v236, v235 row_mirror row_mask:0xf bank_mask:0xf
	v_mov_b32_dpp v238, v237 row_mirror row_mask:0xf bank_mask:0xf
	v_mov_b32_dpp v240, v239 row_mirror row_mask:0xf bank_mask:0xf
	v_mov_b32_dpp v242, v241 row_mirror row_mask:0xf bank_mask:0xf
	v_mov_b32_dpp v244, v243 row_mirror row_mask:0xf bank_mask:0xf
	v_mov_b32_dpp v246, v245 row_mirror row_mask:0xf bank_mask:0xf
	v_mov_b32_dpp v248, v247 row_mirror row_mask:0xf bank_mask:0xf
	s_waitcnt lgkmcnt(0)
	v_add_f32_e32 v235, v235, v236
	s_waitcnt lgkmcnt(0)
	v_add_f32_e32 v237, v237, v238
	s_waitcnt lgkmcnt(0)
	v_add_f32_e32 v239, v239, v240
	s_waitcnt lgkmcnt(0)
	v_add_f32_e32 v241, v241, v242
	s_waitcnt lgkmcnt(0)
	v_add_f32_e32 v243, v243, v244
	s_waitcnt lgkmcnt(0)
	v_add_f32_e32 v245, v245, v246
	s_waitcnt lgkmcnt(0)
	v_add_f32_e32 v247, v247, v248
	ds_bpermute_b32 v236, v229, v235
	ds_bpermute_b32 v238, v229, v237
	ds_bpermute_b32 v240, v229, v239
	ds_bpermute_b32 v242, v229, v241
	ds_bpermute_b32 v244, v229, v243
	ds_bpermute_b32 v246, v229, v245
	ds_bpermute_b32 v248, v229, v247
	s_waitcnt lgkmcnt(6)
	v_add_f32_e32 v235, v235, v236
	s_waitcnt lgkmcnt(5)
	v_add_f32_e32 v237, v237, v238
	s_waitcnt lgkmcnt(4)
	v_add_f32_e32 v239, v239, v240
	s_waitcnt lgkmcnt(3)
	v_add_f32_e32 v241, v241, v242
	s_waitcnt lgkmcnt(2)
	v_add_f32_e32 v243, v243, v244
	s_waitcnt lgkmcnt(1)
	v_add_f32_e32 v245, v245, v246
	s_waitcnt lgkmcnt(0)
	v_add_f32_e32 v247, v247, v248
	ds_bpermute_b32 v234, v230, v221
	ds_bpermute_b32 v236, v230, v235
	ds_bpermute_b32 v238, v230, v237
	ds_bpermute_b32 v240, v230, v239
	ds_bpermute_b32 v242, v230, v241
	ds_bpermute_b32 v244, v230, v243
	ds_bpermute_b32 v246, v230, v245
	ds_bpermute_b32 v248, v230, v247
	s_ashr_i32 s69, s68, 31
	v_pk_mul_f32 v[62:63], v[18:19], v[62:63]
	v_pk_mul_f32 v[60:61], v[16:17], v[60:61]
	v_pk_mul_f32 v[58:59], v[22:23], v[58:59]
	v_pk_mul_f32 v[56:57], v[20:21], v[56:57]
	v_pk_mul_f32 v[54:55], v[26:27], v[54:55]
	v_pk_mul_f32 v[52:53], v[24:25], v[52:53]
	v_pk_mul_f32 v[50:51], v[30:31], v[50:51]
	v_pk_mul_f32 v[48:49], v[28:29], v[48:49]
	s_lshl_b64 s[0:1], s[68:69], 11
	v_pk_mul_f32 v[62:63], v[62:63], v[222:223] op_sel_hi:[1,0]
	v_pk_mul_f32 v[60:61], v[60:61], v[222:223] op_sel_hi:[1,0]
	v_pk_mul_f32 v[58:59], v[58:59], v[222:223] op_sel_hi:[1,0]
	v_pk_mul_f32 v[56:57], v[56:57], v[222:223] op_sel_hi:[1,0]
	v_pk_mul_f32 v[54:55], v[54:55], v[222:223] op_sel_hi:[1,0]
	v_pk_mul_f32 v[52:53], v[52:53], v[222:223] op_sel_hi:[1,0]
	v_pk_mul_f32 v[50:51], v[50:51], v[222:223] op_sel_hi:[1,0]
	v_pk_mul_f32 v[48:49], v[48:49], v[222:223] op_sel_hi:[1,0]
	v_lshl_add_u64 v[250:251], v[214:215], 0, s[0:1]
	v_cvt_pk_bf16_f32 v60, v60, v61
	v_cvt_pk_bf16_f32 v61, v62, v63
	v_cvt_pk_bf16_f32 v56, v56, v57
	v_cvt_pk_bf16_f32 v57, v58, v59
	v_cvt_pk_bf16_f32 v52, v52, v53
	v_cvt_pk_bf16_f32 v53, v54, v55
	v_cvt_pk_bf16_f32 v48, v48, v49
	v_cvt_pk_bf16_f32 v49, v50, v51
	global_store_dwordx2 v[250:251], v[60:61], off
	global_store_dwordx2 v[250:251], v[56:57], off offset:512
	global_store_dwordx2 v[250:251], v[52:53], off offset:1024
	global_store_dwordx2 v[250:251], v[48:49], off offset:1536
	s_and_saveexec_b64 s[70:71], vcc
	s_cbranch_execz .LBB0_112
	global_load_dword v48, v[216:217], off
	s_waitcnt lgkmcnt(7)
	v_add_f32_e32 v56, v221, v234
	s_waitcnt lgkmcnt(6)
	v_add_f32_e32 v55, v235, v236
	v_mul_f32_e32 v56, v222, v56
	s_waitcnt lgkmcnt(5)
	v_add_f32_e32 v54, v237, v238
	v_mul_f32_e32 v55, v222, v55
	v_cndmask_b32_e64 v56, 0, v56, s[8:9]
	s_waitcnt lgkmcnt(4)
	v_add_f32_e32 v53, v239, v240
	v_mul_f32_e32 v54, v222, v54
	v_cndmask_b32_e64 v55, v56, v55, s[10:11]
	s_waitcnt lgkmcnt(3)
	v_add_f32_e32 v52, v241, v242
	v_mul_f32_e32 v53, v222, v53
	v_cndmask_b32_e64 v54, v55, v54, s[12:13]
	s_waitcnt lgkmcnt(2)
	v_add_f32_e32 v51, v243, v244
	v_mul_f32_e32 v52, v222, v52
	v_cndmask_b32_e64 v53, v54, v53, s[14:15]
	s_waitcnt lgkmcnt(1)
	v_add_f32_e32 v50, v245, v246
	v_mul_f32_e32 v51, v222, v51
	v_cndmask_b32_e64 v52, v53, v52, s[16:17]
	s_waitcnt lgkmcnt(0)
	v_add_f32_e32 v49, v247, v248
	v_mul_f32_e32 v50, v222, v50
	v_cndmask_b32_e64 v51, v52, v51, s[18:19]
	v_mul_f32_e32 v49, v222, v49
	v_cndmask_b32_e64 v50, v51, v50, s[20:21]
	v_cndmask_b32_e64 v49, v50, v49, s[22:23]
	s_lshl_b64 s[68:69], s[68:69], 5
	s_waitcnt vmcnt(0)
	v_add_f32_e32 v48, v49, v48
	v_mul_f32_e64 v49, |v48|, s35
	v_exp_f32_e32 v62, v49
	v_min_f32_e32 v63, 0, v48
	v_add_f32_e32 v50, 1.0, v62
	v_add_f32_e32 v51, -1.0, v50
	v_frexp_mant_f32_e32 v52, v50
	v_cvt_f64_f32_e32 v[48:49], v50
	v_sub_f32_e32 v53, v51, v50
	v_frexp_exp_i32_f64_e32 v48, v[48:49]
	v_cmp_gt_f32_e64 s[0:1], s41, v52
	v_sub_f32_e32 v51, v62, v51
	v_add_f32_e32 v49, 1.0, v53
	v_subbrev_co_u32_e64 v48, s[0:1], 0, v48, s[0:1]
	v_add_f32_e32 v49, v51, v49
	v_sub_u32_e32 v51, 0, v48
	v_ldexp_f32 v50, v50, v51
	v_add_f32_e32 v52, -1.0, v50
	v_add_f32_e32 v53, 1.0, v50
	v_ldexp_f32 v49, v49, v51
	v_add_f32_e32 v51, 1.0, v52
	v_add_f32_e32 v54, -1.0, v53
	v_sub_f32_e32 v51, v50, v51
	v_sub_f32_e32 v50, v50, v54
	v_add_f32_e32 v54, v49, v51
	v_add_f32_e32 v49, v49, v50
	v_add_f32_e32 v56, v53, v49
	v_rcp_f32_e32 v57, v56
	v_add_f32_e32 v51, v52, v54
	v_sub_f32_e32 v52, v51, v52
	v_sub_f32_e32 v50, v56, v53
	v_mul_f32_e32 v59, v51, v57
	v_sub_f32_e32 v58, v54, v52
	v_mul_f32_e32 v52, v56, v59
	v_sub_f32_e32 v49, v49, v50
	v_fma_f32 v54, v59, v56, -v52
	v_fmac_f32_e32 v54, v59, v49
	v_add_f32_e32 v50, v52, v54
	v_sub_f32_e32 v53, v51, v50
	v_mov_b32_e32 v55, v50
	v_pk_add_f32 v[50:51], v[50:51], v[52:53] neg_lo:[0,1] neg_hi:[0,1]
	v_cvt_f32_i32_e32 v48, v48
	v_pk_add_f32 v[50:51], v[50:51], v[54:55] neg_lo:[0,1] neg_hi:[0,1]
	v_cmp_neq_f32_e64 s[0:1], s53, v62
	v_add_f32_e32 v51, v58, v51
	v_add_f32_e32 v50, v50, v51
	v_add_f32_e32 v51, v53, v50
	v_mul_f32_e32 v55, v57, v51
	v_mul_f32_e32 v52, v56, v55
	v_sub_f32_e32 v53, v53, v51
	v_add_f32_e32 v60, v59, v55
	v_fma_f32 v54, v55, v56, -v52
	v_add_f32_e32 v58, v50, v53
	v_sub_f32_e32 v50, v60, v59
	v_fmac_f32_e32 v54, v55, v49
	v_sub_f32_e32 v49, v55, v50
	v_add_f32_e32 v50, v52, v54
	v_sub_f32_e32 v53, v51, v50
	v_mov_b32_e32 v55, v50
	v_pk_add_f32 v[50:51], v[50:51], v[52:53] neg_lo:[0,1] neg_hi:[0,1]
	s_nop 0
	v_pk_add_f32 v[50:51], v[50:51], v[54:55] neg_lo:[0,1] neg_hi:[0,1]
	s_nop 0
	v_add_f32_e32 v51, v58, v51
	v_add_f32_e32 v50, v50, v51
	v_add_f32_e32 v50, v53, v50
	v_mul_f32_e32 v50, v57, v50
	v_add_f32_e32 v49, v49, v50
	v_add_f32_e32 v50, v60, v49
	v_mul_f32_e32 v52, v50, v50
	v_sub_f32_e32 v53, v50, v60
	v_fmamk_f32 v54, v52, 0x3e9b6dac, v211
	v_sub_f32_e32 v53, v49, v53
	v_mul_f32_e32 v49, v50, v52
	v_fmaak_f32 v221, v52, v54, 0x3f2aaada
	v_ldexp_f32 v55, v53, 1
	v_pk_mul_f32 v[52:53], v[48:49], v[220:221]
	v_ldexp_f32 v51, v50, 1
	v_fma_f32 v50, v48, s52, -v52
	v_fmac_f32_e32 v50, 0xb102e308, v48
	v_pk_add_f32 v[48:49], v[52:53], v[50:51]
	v_mov_b32_e32 v54, v52
	v_sub_f32_e32 v58, v49, v51
	v_pk_add_f32 v[56:57], v[48:49], v[52:53] neg_lo:[0,1] neg_hi:[0,1]
	v_sub_f32_e32 v52, v53, v58
	v_add_f32_e32 v55, v55, v52
	v_pk_add_f32 v[52:53], v[48:49], v[54:55]
	v_mov_b32_e32 v51, v48
	v_mov_b32_e32 v57, v53
	v_pk_add_f32 v[60:61], v[50:51], v[56:57] neg_lo:[0,1] neg_hi:[0,1]
	v_pk_add_f32 v[50:51], v[50:51], v[56:57]
	v_mov_b32_e32 v59, v48
	v_pk_add_f32 v[56:57], v[50:51], v[48:49] op_sel:[1,0] op_sel_hi:[0,1] neg_lo:[0,1] neg_hi:[0,1]
	v_mov_b32_e32 v58, v55
	v_mov_b32_e32 v54, v53
	v_mov_b32_e32 v55, v51
	v_pk_mov_b32 v[48:49], v[48:49], v[56:57] op_sel:[1,0]
	v_pk_add_f32 v[52:53], v[52:53], v[56:57] op_sel_hi:[1,0] neg_lo:[0,1] neg_hi:[0,1]
	v_pk_add_f32 v[48:49], v[54:55], v[48:49] neg_lo:[0,1] neg_hi:[0,1]
	v_mov_b32_e32 v52, v60
	v_pk_add_f32 v[48:49], v[58:59], v[48:49] neg_lo:[0,1] neg_hi:[0,1]
	v_mov_b32_e32 v61, v51
	v_pk_add_f32 v[52:53], v[52:53], v[48:49]
	s_nop 0
	v_pk_add_f32 v[54:55], v[52:53], v[52:53] op_sel:[0,1] op_sel_hi:[1,0]
	s_nop 0
	v_pk_add_f32 v[50:51], v[50:51], v[54:55] op_sel:[1,0] op_sel_hi:[0,1]
	v_mov_b32_e32 v53, v50
	v_mov_b32_e32 v49, v54
	v_pk_add_f32 v[54:55], v[52:53], v[60:61] neg_lo:[0,1] neg_hi:[0,1]
	s_nop 0
	v_sub_f32_e32 v51, v52, v54
	v_pk_add_f32 v[48:49], v[48:49], v[54:55] neg_lo:[0,1] neg_hi:[0,1]
	v_sub_f32_e32 v51, v60, v51
	v_add_f32_e32 v48, v48, v51
	v_add_f32_e32 v48, v48, v49
	v_add_f32_e32 v48, v50, v48
	v_cndmask_b32_e64 v48, v231, v48, s[0:1]
	v_cmp_ngt_f32_e64 s[0:1], -1.0, v62
	s_nop 1
	v_cndmask_b32_e64 v48, v232, v48, s[0:1]
	v_cmp_neq_f32_e64 s[0:1], -1.0, v62
	s_nop 1
	v_cndmask_b32_e64 v48, v233, v48, s[0:1]
	v_cmp_lt_f32_e64 s[0:1], |v62|, s54
	s_nop 1
	v_cndmask_b32_e64 v48, v48, v62, s[0:1]
	v_sub_f32_e32 v50, v63, v48
	v_lshl_add_u64 v[48:49], v[218:219], 0, s[68:69]
	global_store_dword v[48:49], v50, off
	s_branch .LBB0_112
